# P4 row pass rewritten by hand: gain vector loaded once per phase, all row loads up front, stores never waited, DPP/readlane wave sums instead of ds_bpermute chains
# speedup vs baseline: 1.2504x; 1.0105x over previous
.LBB0_458:
	s_or_b64 exec, exec, s[0:1]
	v_readlane_b32 s0, v244, 22
	v_readlane_b32 s1, v244, 23
	s_waitcnt lgkmcnt(0)
	v_mov_b32_e32 v0, v214
	s_andn2_b64 vcc, exec, s[0:1]
	v_cndmask_b32_e64 v1, 0, 1, s[0:1]
	v_cmp_ne_u32_e64 s[80:81], 1, v1
	s_barrier
	s_cbranch_vccnz .LBB0_469
	v_and_b32_e32 v1, 63, v214
	v_lshlrev_b32_e32 v2, 3, v1
	v_lshlrev_b32_e32 v5, 4, v1
	v_add_u32_e32 v3, 0x2000000, v2
	v_add_u32_e32 v4, 0x18800000, v2
	v_add_u32_e32 v2, 0x8000000, v2
	v_mov_b32_e32 v6, 0x1f00000
	v_mov_b32_e32 v143, 0x358637bd
	global_load_dwordx4 v[80:83], v5, s[22:23] offset:0
	global_load_dwordx4 v[84:87], v5, s[22:23] offset:1024
	global_load_dwordx4 v[88:91], v5, s[22:23] offset:2048
	global_load_dwordx4 v[92:95], v5, s[22:23] offset:3072
	s_lshl_b32 s5, s66, 3
	s_mov_b32 s35, s68
.Lp4_loop:
	s_lshl_b32 s0, s35, 11
	s_add_u32 s8, s74, s0
	s_addc_u32 s9, s75, 0
	global_load_dwordx2 v[16:17], v2, s[8:9] offset:0 nt
	global_load_dwordx2 v[18:19], v2, s[8:9] offset:512 nt
	global_load_dwordx2 v[20:21], v2, s[8:9] offset:1024 nt
	global_load_dwordx2 v[22:23], v2, s[8:9] offset:1536 nt
	global_load_dwordx2 v[24:25], v3, s[8:9] offset:0 nt
	global_load_dwordx2 v[26:27], v3, s[8:9] offset:512 nt
	global_load_dwordx2 v[28:29], v3, s[8:9] offset:1024 nt
	global_load_dwordx2 v[30:31], v3, s[8:9] offset:1536 nt
	s_mul_i32 s0, s5, 1
	s_add_i32 s0, s0, s35
	s_lshl_b32 s0, s0, 11
	s_add_u32 s10, s74, s0
	s_addc_u32 s11, s75, 0
	global_load_dwordx2 v[32:33], v2, s[10:11] offset:0 nt
	global_load_dwordx2 v[34:35], v2, s[10:11] offset:512 nt
	global_load_dwordx2 v[36:37], v2, s[10:11] offset:1024 nt
	global_load_dwordx2 v[38:39], v2, s[10:11] offset:1536 nt
	global_load_dwordx2 v[40:41], v3, s[10:11] offset:0 nt
	global_load_dwordx2 v[42:43], v3, s[10:11] offset:512 nt
	global_load_dwordx2 v[44:45], v3, s[10:11] offset:1024 nt
	global_load_dwordx2 v[46:47], v3, s[10:11] offset:1536 nt
	s_mul_i32 s0, s5, 2
	s_add_i32 s0, s0, s35
	s_lshl_b32 s0, s0, 11
	s_add_u32 s12, s74, s0
	s_addc_u32 s13, s75, 0
	global_load_dwordx2 v[48:49], v2, s[12:13] offset:0 nt
	global_load_dwordx2 v[50:51], v2, s[12:13] offset:512 nt
	global_load_dwordx2 v[52:53], v2, s[12:13] offset:1024 nt
	global_load_dwordx2 v[54:55], v2, s[12:13] offset:1536 nt
	global_load_dwordx2 v[56:57], v3, s[12:13] offset:0 nt
	global_load_dwordx2 v[58:59], v3, s[12:13] offset:512 nt
	global_load_dwordx2 v[60:61], v3, s[12:13] offset:1024 nt
	global_load_dwordx2 v[62:63], v3, s[12:13] offset:1536 nt
	s_mul_i32 s0, s5, 3
	s_add_i32 s0, s0, s35
	s_lshl_b32 s0, s0, 11
	s_add_u32 s16, s74, s0
	s_addc_u32 s17, s75, 0
	global_load_dwordx2 v[64:65], v2, s[16:17] offset:0 nt
	global_load_dwordx2 v[66:67], v2, s[16:17] offset:512 nt
	global_load_dwordx2 v[68:69], v2, s[16:17] offset:1024 nt
	global_load_dwordx2 v[70:71], v2, s[16:17] offset:1536 nt
	global_load_dwordx2 v[72:73], v3, s[16:17] offset:0 nt
	global_load_dwordx2 v[74:75], v3, s[16:17] offset:512 nt
	global_load_dwordx2 v[76:77], v3, s[16:17] offset:1024 nt
	global_load_dwordx2 v[78:79], v3, s[16:17] offset:1536 nt
	s_waitcnt vmcnt(24)
	v_lshlrev_b32_e32 v96, 16, v16
	v_and_b32_e32 v97, 0xffff0000, v16
	v_lshlrev_b32_e32 v98, 16, v17
	v_and_b32_e32 v99, 0xffff0000, v17
	v_lshlrev_b32_e32 v100, 16, v18
	v_and_b32_e32 v101, 0xffff0000, v18
	v_lshlrev_b32_e32 v102, 16, v19
	v_and_b32_e32 v103, 0xffff0000, v19
	v_lshlrev_b32_e32 v104, 16, v20
	v_and_b32_e32 v105, 0xffff0000, v20
	v_lshlrev_b32_e32 v106, 16, v21
	v_and_b32_e32 v107, 0xffff0000, v21
	v_lshlrev_b32_e32 v108, 16, v22
	v_and_b32_e32 v109, 0xffff0000, v22
	v_lshlrev_b32_e32 v110, 16, v23
	v_and_b32_e32 v111, 0xffff0000, v23
	v_mul_f32_e32 v129, v97, v97
	v_mul_f32_e32 v130, v99, v99
	v_fmac_f32_e32 v129, v96, v96
	v_fmac_f32_e32 v130, v98, v98
	v_add_f32_e32 v128, v129, v130
	v_mul_f32_e32 v129, v101, v101
	v_mul_f32_e32 v130, v103, v103
	v_fmac_f32_e32 v129, v100, v100
	v_fmac_f32_e32 v130, v102, v102
	v_add_f32_e32 v129, v129, v130
	v_add_f32_e32 v128, v128, v129
	v_mul_f32_e32 v129, v105, v105
	v_mul_f32_e32 v130, v107, v107
	v_fmac_f32_e32 v129, v104, v104
	v_fmac_f32_e32 v130, v106, v106
	v_add_f32_e32 v129, v129, v130
	v_add_f32_e32 v128, v128, v129
	v_mul_f32_e32 v129, v109, v109
	v_mul_f32_e32 v130, v111, v111
	v_fmac_f32_e32 v129, v108, v108
	v_fmac_f32_e32 v130, v110, v110
	v_add_f32_e32 v129, v129, v130
	v_add_f32_e32 v128, v128, v129
	v_lshlrev_b32_e32 v112, 16, v24
	v_and_b32_e32 v113, 0xffff0000, v24
	v_lshlrev_b32_e32 v114, 16, v25
	v_and_b32_e32 v115, 0xffff0000, v25
	v_lshlrev_b32_e32 v116, 16, v26
	v_and_b32_e32 v117, 0xffff0000, v26
	v_lshlrev_b32_e32 v118, 16, v27
	v_and_b32_e32 v119, 0xffff0000, v27
	v_lshlrev_b32_e32 v120, 16, v28
	v_and_b32_e32 v121, 0xffff0000, v28
	v_lshlrev_b32_e32 v122, 16, v29
	v_and_b32_e32 v123, 0xffff0000, v29
	v_lshlrev_b32_e32 v124, 16, v30
	v_and_b32_e32 v125, 0xffff0000, v30
	v_lshlrev_b32_e32 v126, 16, v31
	v_and_b32_e32 v127, 0xffff0000, v31
	v_add_f32_dpp v128, v128, v128 quad_perm:[1,0,3,2] row_mask:0xf bank_mask:0xf
	s_nop 1
	v_add_f32_dpp v128, v128, v128 quad_perm:[2,3,0,1] row_mask:0xf bank_mask:0xf
	s_nop 1
	v_add_f32_dpp v128, v128, v128 row_half_mirror row_mask:0xf bank_mask:0xf
	s_nop 1
	v_add_f32_dpp v128, v128, v128 row_mirror row_mask:0xf bank_mask:0xf
	s_nop 0
	v_readlane_b32 s24, v128, 0
	v_readlane_b32 s25, v128, 16
	v_readlane_b32 s26, v128, 32
	v_readlane_b32 s27, v128, 48
	v_mov_b32_e32 v129, s24
	v_mov_b32_e32 v130, s26
	v_add_f32_e32 v129, s25, v129
	v_add_f32_e32 v130, s27, v130
	v_add_f32_e32 v128, v129, v130
	v_fmamk_f32 v128, v128, 0x3a800000, v143
	v_sqrt_f32_e32 v132, v128
	s_nop 0
	v_add_u32_e32 v133, -1, v132
	v_add_u32_e32 v134, 1, v132
	v_fma_f32 v135, -v133, v132, v128
	v_fma_f32 v136, -v134, v132, v128
	v_cmp_ge_f32_e64 s[20:21], 0, v135
	s_nop 1
	v_cndmask_b32_e64 v132, v132, v133, s[20:21]
	v_cmp_lt_f32_e64 s[20:21], 0, v136
	s_nop 1
	v_cndmask_b32_e64 v132, v132, v134, s[20:21]
	v_div_scale_f32 v133, s[20:21], v132, v132, 1.0
	v_rcp_f32_e32 v134, v133
	v_div_scale_f32 v135, vcc, 1.0, v132, 1.0
	v_fma_f32 v136, -v133, v134, 1.0
	v_fmac_f32_e32 v134, v136, v134
	v_mul_f32_e32 v136, v135, v134
	v_fma_f32 v137, -v133, v136, v135
	v_fmac_f32_e32 v136, v137, v134
	v_fma_f32 v133, -v133, v136, v135
	s_nop 1
	v_div_fmas_f32 v133, v133, v134, v136
	v_div_fixup_f32 v128, v133, v132, 1.0
	v_pk_mul_f32 v[96:97], v[96:97], v[128:129] op_sel_hi:[1,0]
	v_pk_mul_f32 v[98:99], v[98:99], v[128:129] op_sel_hi:[1,0]
	v_pk_mul_f32 v[100:101], v[100:101], v[128:129] op_sel_hi:[1,0]
	v_pk_mul_f32 v[102:103], v[102:103], v[128:129] op_sel_hi:[1,0]
	v_pk_mul_f32 v[104:105], v[104:105], v[128:129] op_sel_hi:[1,0]
	v_pk_mul_f32 v[106:107], v[106:107], v[128:129] op_sel_hi:[1,0]
	v_pk_mul_f32 v[108:109], v[108:109], v[128:129] op_sel_hi:[1,0]
	v_pk_mul_f32 v[110:111], v[110:111], v[128:129] op_sel_hi:[1,0]
	v_pk_fma_f32 v[112:113], v[80:81], v[96:97], v[112:113]
	v_pk_fma_f32 v[114:115], v[82:83], v[98:99], v[114:115]
	v_pk_fma_f32 v[116:117], v[84:85], v[100:101], v[116:117]
	v_pk_fma_f32 v[118:119], v[86:87], v[102:103], v[118:119]
	v_pk_fma_f32 v[120:121], v[88:89], v[104:105], v[120:121]
	v_pk_fma_f32 v[122:123], v[90:91], v[106:107], v[122:123]
	v_pk_fma_f32 v[124:125], v[92:93], v[108:109], v[124:125]
	v_pk_fma_f32 v[126:127], v[94:95], v[110:111], v[126:127]
	v_cvt_pk_bf16_f32 v16, v112, v113
	v_cvt_pk_bf16_f32 v17, v114, v115
	v_cvt_pk_bf16_f32 v18, v116, v117
	v_cvt_pk_bf16_f32 v19, v118, v119
	v_cvt_pk_bf16_f32 v20, v120, v121
	v_cvt_pk_bf16_f32 v21, v122, v123
	v_cvt_pk_bf16_f32 v22, v124, v125
	v_cvt_pk_bf16_f32 v23, v126, v127
	global_store_dwordx2 v4, v[16:17], s[8:9] offset:0
	global_store_dwordx2 v4, v[18:19], s[8:9] offset:512
	global_store_dwordx2 v4, v[20:21], s[8:9] offset:1024
	global_store_dwordx2 v4, v[22:23], s[8:9] offset:1536
	v_mul_f32_e32 v141, v113, v113
	v_mul_f32_e32 v142, v115, v115
	v_fmac_f32_e32 v141, v112, v112
	v_fmac_f32_e32 v142, v114, v114
	v_add_f32_e32 v140, v141, v142
	v_mul_f32_e32 v141, v117, v117
	v_mul_f32_e32 v142, v119, v119
	v_fmac_f32_e32 v141, v116, v116
	v_fmac_f32_e32 v142, v118, v118
	v_add_f32_e32 v141, v141, v142
	v_add_f32_e32 v140, v140, v141
	v_mul_f32_e32 v141, v121, v121
	v_mul_f32_e32 v142, v123, v123
	v_fmac_f32_e32 v141, v120, v120
	v_fmac_f32_e32 v142, v122, v122
	v_add_f32_e32 v141, v141, v142
	v_add_f32_e32 v140, v140, v141
	v_mul_f32_e32 v141, v125, v125
	v_mul_f32_e32 v142, v127, v127
	v_fmac_f32_e32 v141, v124, v124
	v_fmac_f32_e32 v142, v126, v126
	v_add_f32_e32 v141, v141, v142
	v_add_f32_e32 v140, v140, v141
	s_nop 1
	v_add_f32_dpp v140, v140, v140 quad_perm:[1,0,3,2] row_mask:0xf bank_mask:0xf
	s_nop 1
	v_add_f32_dpp v140, v140, v140 quad_perm:[2,3,0,1] row_mask:0xf bank_mask:0xf
	s_nop 1
	v_add_f32_dpp v140, v140, v140 row_half_mirror row_mask:0xf bank_mask:0xf
	s_nop 1
	v_add_f32_dpp v140, v140, v140 row_mirror row_mask:0xf bank_mask:0xf
	s_nop 0
	v_readlane_b32 s24, v140, 0
	v_readlane_b32 s25, v140, 16
	v_readlane_b32 s26, v140, 32
	v_readlane_b32 s27, v140, 48
	v_mov_b32_e32 v141, s24
	v_mov_b32_e32 v142, s26
	v_add_f32_e32 v141, s25, v141
	v_add_f32_e32 v142, s27, v142
	v_add_f32_e32 v140, v141, v142
	v_fmamk_f32 v140, v140, 0x3a800000, v143
	v_sqrt_f32_e32 v132, v140
	s_nop 0
	v_add_u32_e32 v133, -1, v132
	v_add_u32_e32 v134, 1, v132
	v_fma_f32 v135, -v133, v132, v140
	v_fma_f32 v136, -v134, v132, v140
	v_cmp_ge_f32_e64 s[20:21], 0, v135
	s_nop 1
	v_cndmask_b32_e64 v132, v132, v133, s[20:21]
	v_cmp_lt_f32_e64 s[20:21], 0, v136
	s_nop 1
	v_cndmask_b32_e64 v132, v132, v134, s[20:21]
	v_div_scale_f32 v133, s[20:21], v132, v132, 1.0
	v_rcp_f32_e32 v134, v133
	v_div_scale_f32 v135, vcc, 1.0, v132, 1.0
	v_fma_f32 v136, -v133, v134, 1.0
	v_fmac_f32_e32 v134, v136, v134
	v_mul_f32_e32 v136, v135, v134
	v_fma_f32 v137, -v133, v136, v135
	v_fmac_f32_e32 v136, v137, v134
	v_fma_f32 v133, -v133, v136, v135
	s_nop 1
	v_div_fmas_f32 v133, v133, v134, v136
	v_div_fixup_f32 v140, v133, v132, 1.0
	s_lshl_b32 s0, s35, 2
	s_add_u32 s18, s74, s0
	s_addc_u32 s19, s75, 0
	s_mov_b64 s[30:31], exec
	s_mov_b64 exec, 1
	global_store_dword v6, v140, s[18:19]
	s_mov_b64 exec, s[30:31]
	s_waitcnt vmcnt(21)
	v_lshlrev_b32_e32 v96, 16, v32
	v_and_b32_e32 v97, 0xffff0000, v32
	v_lshlrev_b32_e32 v98, 16, v33
	v_and_b32_e32 v99, 0xffff0000, v33
	v_lshlrev_b32_e32 v100, 16, v34
	v_and_b32_e32 v101, 0xffff0000, v34
	v_lshlrev_b32_e32 v102, 16, v35
	v_and_b32_e32 v103, 0xffff0000, v35
	v_lshlrev_b32_e32 v104, 16, v36
	v_and_b32_e32 v105, 0xffff0000, v36
	v_lshlrev_b32_e32 v106, 16, v37
	v_and_b32_e32 v107, 0xffff0000, v37
	v_lshlrev_b32_e32 v108, 16, v38
	v_and_b32_e32 v109, 0xffff0000, v38
	v_lshlrev_b32_e32 v110, 16, v39
	v_and_b32_e32 v111, 0xffff0000, v39
	v_mul_f32_e32 v129, v97, v97
	v_mul_f32_e32 v130, v99, v99
	v_fmac_f32_e32 v129, v96, v96
	v_fmac_f32_e32 v130, v98, v98
	v_add_f32_e32 v128, v129, v130
	v_mul_f32_e32 v129, v101, v101
	v_mul_f32_e32 v130, v103, v103
	v_fmac_f32_e32 v129, v100, v100
	v_fmac_f32_e32 v130, v102, v102
	v_add_f32_e32 v129, v129, v130
	v_add_f32_e32 v128, v128, v129
	v_mul_f32_e32 v129, v105, v105
	v_mul_f32_e32 v130, v107, v107
	v_fmac_f32_e32 v129, v104, v104
	v_fmac_f32_e32 v130, v106, v106
	v_add_f32_e32 v129, v129, v130
	v_add_f32_e32 v128, v128, v129
	v_mul_f32_e32 v129, v109, v109
	v_mul_f32_e32 v130, v111, v111
	v_fmac_f32_e32 v129, v108, v108
	v_fmac_f32_e32 v130, v110, v110
	v_add_f32_e32 v129, v129, v130
	v_add_f32_e32 v128, v128, v129
	v_lshlrev_b32_e32 v112, 16, v40
	v_and_b32_e32 v113, 0xffff0000, v40
	v_lshlrev_b32_e32 v114, 16, v41
	v_and_b32_e32 v115, 0xffff0000, v41
	v_lshlrev_b32_e32 v116, 16, v42
	v_and_b32_e32 v117, 0xffff0000, v42
	v_lshlrev_b32_e32 v118, 16, v43
	v_and_b32_e32 v119, 0xffff0000, v43
	v_lshlrev_b32_e32 v120, 16, v44
	v_and_b32_e32 v121, 0xffff0000, v44
	v_lshlrev_b32_e32 v122, 16, v45
	v_and_b32_e32 v123, 0xffff0000, v45
	v_lshlrev_b32_e32 v124, 16, v46
	v_and_b32_e32 v125, 0xffff0000, v46
	v_lshlrev_b32_e32 v126, 16, v47
	v_and_b32_e32 v127, 0xffff0000, v47
	v_add_f32_dpp v128, v128, v128 quad_perm:[1,0,3,2] row_mask:0xf bank_mask:0xf
	s_nop 1
	v_add_f32_dpp v128, v128, v128 quad_perm:[2,3,0,1] row_mask:0xf bank_mask:0xf
	s_nop 1
	v_add_f32_dpp v128, v128, v128 row_half_mirror row_mask:0xf bank_mask:0xf
	s_nop 1
	v_add_f32_dpp v128, v128, v128 row_mirror row_mask:0xf bank_mask:0xf
	s_nop 0
	v_readlane_b32 s24, v128, 0
	v_readlane_b32 s25, v128, 16
	v_readlane_b32 s26, v128, 32
	v_readlane_b32 s27, v128, 48
	v_mov_b32_e32 v129, s24
	v_mov_b32_e32 v130, s26
	v_add_f32_e32 v129, s25, v129
	v_add_f32_e32 v130, s27, v130
	v_add_f32_e32 v128, v129, v130
	v_fmamk_f32 v128, v128, 0x3a800000, v143
	v_sqrt_f32_e32 v132, v128
	s_nop 0
	v_add_u32_e32 v133, -1, v132
	v_add_u32_e32 v134, 1, v132
	v_fma_f32 v135, -v133, v132, v128
	v_fma_f32 v136, -v134, v132, v128
	v_cmp_ge_f32_e64 s[20:21], 0, v135
	s_nop 1
	v_cndmask_b32_e64 v132, v132, v133, s[20:21]
	v_cmp_lt_f32_e64 s[20:21], 0, v136
	s_nop 1
	v_cndmask_b32_e64 v132, v132, v134, s[20:21]
	v_div_scale_f32 v133, s[20:21], v132, v132, 1.0
	v_rcp_f32_e32 v134, v133
	v_div_scale_f32 v135, vcc, 1.0, v132, 1.0
	v_fma_f32 v136, -v133, v134, 1.0
	v_fmac_f32_e32 v134, v136, v134
	v_mul_f32_e32 v136, v135, v134
	v_fma_f32 v137, -v133, v136, v135
	v_fmac_f32_e32 v136, v137, v134
	v_fma_f32 v133, -v133, v136, v135
	s_nop 1
	v_div_fmas_f32 v133, v133, v134, v136
	v_div_fixup_f32 v128, v133, v132, 1.0
	v_pk_mul_f32 v[96:97], v[96:97], v[128:129] op_sel_hi:[1,0]
	v_pk_mul_f32 v[98:99], v[98:99], v[128:129] op_sel_hi:[1,0]
	v_pk_mul_f32 v[100:101], v[100:101], v[128:129] op_sel_hi:[1,0]
	v_pk_mul_f32 v[102:103], v[102:103], v[128:129] op_sel_hi:[1,0]
	v_pk_mul_f32 v[104:105], v[104:105], v[128:129] op_sel_hi:[1,0]
	v_pk_mul_f32 v[106:107], v[106:107], v[128:129] op_sel_hi:[1,0]
	v_pk_mul_f32 v[108:109], v[108:109], v[128:129] op_sel_hi:[1,0]
	v_pk_mul_f32 v[110:111], v[110:111], v[128:129] op_sel_hi:[1,0]
	v_pk_fma_f32 v[112:113], v[80:81], v[96:97], v[112:113]
	v_pk_fma_f32 v[114:115], v[82:83], v[98:99], v[114:115]
	v_pk_fma_f32 v[116:117], v[84:85], v[100:101], v[116:117]
	v_pk_fma_f32 v[118:119], v[86:87], v[102:103], v[118:119]
	v_pk_fma_f32 v[120:121], v[88:89], v[104:105], v[120:121]
	v_pk_fma_f32 v[122:123], v[90:91], v[106:107], v[122:123]
	v_pk_fma_f32 v[124:125], v[92:93], v[108:109], v[124:125]
	v_pk_fma_f32 v[126:127], v[94:95], v[110:111], v[126:127]
	v_cvt_pk_bf16_f32 v32, v112, v113
	v_cvt_pk_bf16_f32 v33, v114, v115
	v_cvt_pk_bf16_f32 v34, v116, v117
	v_cvt_pk_bf16_f32 v35, v118, v119
	v_cvt_pk_bf16_f32 v36, v120, v121
	v_cvt_pk_bf16_f32 v37, v122, v123
	v_cvt_pk_bf16_f32 v38, v124, v125
	v_cvt_pk_bf16_f32 v39, v126, v127
	global_store_dwordx2 v4, v[32:33], s[10:11] offset:0
	global_store_dwordx2 v4, v[34:35], s[10:11] offset:512
	global_store_dwordx2 v4, v[36:37], s[10:11] offset:1024
	global_store_dwordx2 v4, v[38:39], s[10:11] offset:1536
	v_mul_f32_e32 v141, v113, v113
	v_mul_f32_e32 v142, v115, v115
	v_fmac_f32_e32 v141, v112, v112
	v_fmac_f32_e32 v142, v114, v114
	v_add_f32_e32 v140, v141, v142
	v_mul_f32_e32 v141, v117, v117
	v_mul_f32_e32 v142, v119, v119
	v_fmac_f32_e32 v141, v116, v116
	v_fmac_f32_e32 v142, v118, v118
	v_add_f32_e32 v141, v141, v142
	v_add_f32_e32 v140, v140, v141
	v_mul_f32_e32 v141, v121, v121
	v_mul_f32_e32 v142, v123, v123
	v_fmac_f32_e32 v141, v120, v120
	v_fmac_f32_e32 v142, v122, v122
	v_add_f32_e32 v141, v141, v142
	v_add_f32_e32 v140, v140, v141
	v_mul_f32_e32 v141, v125, v125
	v_mul_f32_e32 v142, v127, v127
	v_fmac_f32_e32 v141, v124, v124
	v_fmac_f32_e32 v142, v126, v126
	v_add_f32_e32 v141, v141, v142
	v_add_f32_e32 v140, v140, v141
	s_nop 1
	v_add_f32_dpp v140, v140, v140 quad_perm:[1,0,3,2] row_mask:0xf bank_mask:0xf
	s_nop 1
	v_add_f32_dpp v140, v140, v140 quad_perm:[2,3,0,1] row_mask:0xf bank_mask:0xf
	s_nop 1
	v_add_f32_dpp v140, v140, v140 row_half_mirror row_mask:0xf bank_mask:0xf
	s_nop 1
	v_add_f32_dpp v140, v140, v140 row_mirror row_mask:0xf bank_mask:0xf
	s_nop 0
	v_readlane_b32 s24, v140, 0
	v_readlane_b32 s25, v140, 16
	v_readlane_b32 s26, v140, 32
	v_readlane_b32 s27, v140, 48
	v_mov_b32_e32 v141, s24
	v_mov_b32_e32 v142, s26
	v_add_f32_e32 v141, s25, v141
	v_add_f32_e32 v142, s27, v142
	v_add_f32_e32 v140, v141, v142
	v_fmamk_f32 v140, v140, 0x3a800000, v143
	v_sqrt_f32_e32 v132, v140
	s_nop 0
	v_add_u32_e32 v133, -1, v132
	v_add_u32_e32 v134, 1, v132
	v_fma_f32 v135, -v133, v132, v140
	v_fma_f32 v136, -v134, v132, v140
	v_cmp_ge_f32_e64 s[20:21], 0, v135
	s_nop 1
	v_cndmask_b32_e64 v132, v132, v133, s[20:21]
	v_cmp_lt_f32_e64 s[20:21], 0, v136
	s_nop 1
	v_cndmask_b32_e64 v132, v132, v134, s[20:21]
	v_div_scale_f32 v133, s[20:21], v132, v132, 1.0
	v_rcp_f32_e32 v134, v133
	v_div_scale_f32 v135, vcc, 1.0, v132, 1.0
	v_fma_f32 v136, -v133, v134, 1.0
	v_fmac_f32_e32 v134, v136, v134
	v_mul_f32_e32 v136, v135, v134
	v_fma_f32 v137, -v133, v136, v135
	v_fmac_f32_e32 v136, v137, v134
	v_fma_f32 v133, -v133, v136, v135
	s_nop 1
	v_div_fmas_f32 v133, v133, v134, v136
	v_div_fixup_f32 v140, v133, v132, 1.0
	s_mul_i32 s0, s5, 1
	s_add_i32 s0, s0, s35
	s_lshl_b32 s0, s0, 2
	s_add_u32 s18, s74, s0
	s_addc_u32 s19, s75, 0
	s_mov_b64 s[30:31], exec
	s_mov_b64 exec, 1
	global_store_dword v6, v140, s[18:19]
	s_mov_b64 exec, s[30:31]
	s_waitcnt vmcnt(18)
	v_lshlrev_b32_e32 v96, 16, v48
	v_and_b32_e32 v97, 0xffff0000, v48
	v_lshlrev_b32_e32 v98, 16, v49
	v_and_b32_e32 v99, 0xffff0000, v49
	v_lshlrev_b32_e32 v100, 16, v50
	v_and_b32_e32 v101, 0xffff0000, v50
	v_lshlrev_b32_e32 v102, 16, v51
	v_and_b32_e32 v103, 0xffff0000, v51
	v_lshlrev_b32_e32 v104, 16, v52
	v_and_b32_e32 v105, 0xffff0000, v52
	v_lshlrev_b32_e32 v106, 16, v53
	v_and_b32_e32 v107, 0xffff0000, v53
	v_lshlrev_b32_e32 v108, 16, v54
	v_and_b32_e32 v109, 0xffff0000, v54
	v_lshlrev_b32_e32 v110, 16, v55
	v_and_b32_e32 v111, 0xffff0000, v55
	v_mul_f32_e32 v129, v97, v97
	v_mul_f32_e32 v130, v99, v99
	v_fmac_f32_e32 v129, v96, v96
	v_fmac_f32_e32 v130, v98, v98
	v_add_f32_e32 v128, v129, v130
	v_mul_f32_e32 v129, v101, v101
	v_mul_f32_e32 v130, v103, v103
	v_fmac_f32_e32 v129, v100, v100
	v_fmac_f32_e32 v130, v102, v102
	v_add_f32_e32 v129, v129, v130
	v_add_f32_e32 v128, v128, v129
	v_mul_f32_e32 v129, v105, v105
	v_mul_f32_e32 v130, v107, v107
	v_fmac_f32_e32 v129, v104, v104
	v_fmac_f32_e32 v130, v106, v106
	v_add_f32_e32 v129, v129, v130
	v_add_f32_e32 v128, v128, v129
	v_mul_f32_e32 v129, v109, v109
	v_mul_f32_e32 v130, v111, v111
	v_fmac_f32_e32 v129, v108, v108
	v_fmac_f32_e32 v130, v110, v110
	v_add_f32_e32 v129, v129, v130
	v_add_f32_e32 v128, v128, v129
	v_lshlrev_b32_e32 v112, 16, v56
	v_and_b32_e32 v113, 0xffff0000, v56
	v_lshlrev_b32_e32 v114, 16, v57
	v_and_b32_e32 v115, 0xffff0000, v57
	v_lshlrev_b32_e32 v116, 16, v58
	v_and_b32_e32 v117, 0xffff0000, v58
	v_lshlrev_b32_e32 v118, 16, v59
	v_and_b32_e32 v119, 0xffff0000, v59
	v_lshlrev_b32_e32 v120, 16, v60
	v_and_b32_e32 v121, 0xffff0000, v60
	v_lshlrev_b32_e32 v122, 16, v61
	v_and_b32_e32 v123, 0xffff0000, v61
	v_lshlrev_b32_e32 v124, 16, v62
	v_and_b32_e32 v125, 0xffff0000, v62
	v_lshlrev_b32_e32 v126, 16, v63
	v_and_b32_e32 v127, 0xffff0000, v63
	v_add_f32_dpp v128, v128, v128 quad_perm:[1,0,3,2] row_mask:0xf bank_mask:0xf
	s_nop 1
	v_add_f32_dpp v128, v128, v128 quad_perm:[2,3,0,1] row_mask:0xf bank_mask:0xf
	s_nop 1
	v_add_f32_dpp v128, v128, v128 row_half_mirror row_mask:0xf bank_mask:0xf
	s_nop 1
	v_add_f32_dpp v128, v128, v128 row_mirror row_mask:0xf bank_mask:0xf
	s_nop 0
	v_readlane_b32 s24, v128, 0
	v_readlane_b32 s25, v128, 16
	v_readlane_b32 s26, v128, 32
	v_readlane_b32 s27, v128, 48
	v_mov_b32_e32 v129, s24
	v_mov_b32_e32 v130, s26
	v_add_f32_e32 v129, s25, v129
	v_add_f32_e32 v130, s27, v130
	v_add_f32_e32 v128, v129, v130
	v_fmamk_f32 v128, v128, 0x3a800000, v143
	v_sqrt_f32_e32 v132, v128
	s_nop 0
	v_add_u32_e32 v133, -1, v132
	v_add_u32_e32 v134, 1, v132
	v_fma_f32 v135, -v133, v132, v128
	v_fma_f32 v136, -v134, v132, v128
	v_cmp_ge_f32_e64 s[20:21], 0, v135
	s_nop 1
	v_cndmask_b32_e64 v132, v132, v133, s[20:21]
	v_cmp_lt_f32_e64 s[20:21], 0, v136
	s_nop 1
	v_cndmask_b32_e64 v132, v132, v134, s[20:21]
	v_div_scale_f32 v133, s[20:21], v132, v132, 1.0
	v_rcp_f32_e32 v134, v133
	v_div_scale_f32 v135, vcc, 1.0, v132, 1.0
	v_fma_f32 v136, -v133, v134, 1.0
	v_fmac_f32_e32 v134, v136, v134
	v_mul_f32_e32 v136, v135, v134
	v_fma_f32 v137, -v133, v136, v135
	v_fmac_f32_e32 v136, v137, v134
	v_fma_f32 v133, -v133, v136, v135
	s_nop 1
	v_div_fmas_f32 v133, v133, v134, v136
	v_div_fixup_f32 v128, v133, v132, 1.0
	v_pk_mul_f32 v[96:97], v[96:97], v[128:129] op_sel_hi:[1,0]
	v_pk_mul_f32 v[98:99], v[98:99], v[128:129] op_sel_hi:[1,0]
	v_pk_mul_f32 v[100:101], v[100:101], v[128:129] op_sel_hi:[1,0]
	v_pk_mul_f32 v[102:103], v[102:103], v[128:129] op_sel_hi:[1,0]
	v_pk_mul_f32 v[104:105], v[104:105], v[128:129] op_sel_hi:[1,0]
	v_pk_mul_f32 v[106:107], v[106:107], v[128:129] op_sel_hi:[1,0]
	v_pk_mul_f32 v[108:109], v[108:109], v[128:129] op_sel_hi:[1,0]
	v_pk_mul_f32 v[110:111], v[110:111], v[128:129] op_sel_hi:[1,0]
	v_pk_fma_f32 v[112:113], v[80:81], v[96:97], v[112:113]
	v_pk_fma_f32 v[114:115], v[82:83], v[98:99], v[114:115]
	v_pk_fma_f32 v[116:117], v[84:85], v[100:101], v[116:117]
	v_pk_fma_f32 v[118:119], v[86:87], v[102:103], v[118:119]
	v_pk_fma_f32 v[120:121], v[88:89], v[104:105], v[120:121]
	v_pk_fma_f32 v[122:123], v[90:91], v[106:107], v[122:123]
	v_pk_fma_f32 v[124:125], v[92:93], v[108:109], v[124:125]
	v_pk_fma_f32 v[126:127], v[94:95], v[110:111], v[126:127]
	v_cvt_pk_bf16_f32 v48, v112, v113
	v_cvt_pk_bf16_f32 v49, v114, v115
	v_cvt_pk_bf16_f32 v50, v116, v117
	v_cvt_pk_bf16_f32 v51, v118, v119
	v_cvt_pk_bf16_f32 v52, v120, v121
	v_cvt_pk_bf16_f32 v53, v122, v123
	v_cvt_pk_bf16_f32 v54, v124, v125
	v_cvt_pk_bf16_f32 v55, v126, v127
	global_store_dwordx2 v4, v[48:49], s[12:13] offset:0
	global_store_dwordx2 v4, v[50:51], s[12:13] offset:512
	global_store_dwordx2 v4, v[52:53], s[12:13] offset:1024
	global_store_dwordx2 v4, v[54:55], s[12:13] offset:1536
	v_mul_f32_e32 v141, v113, v113
	v_mul_f32_e32 v142, v115, v115
	v_fmac_f32_e32 v141, v112, v112
	v_fmac_f32_e32 v142, v114, v114
	v_add_f32_e32 v140, v141, v142
	v_mul_f32_e32 v141, v117, v117
	v_mul_f32_e32 v142, v119, v119
	v_fmac_f32_e32 v141, v116, v116
	v_fmac_f32_e32 v142, v118, v118
	v_add_f32_e32 v141, v141, v142
	v_add_f32_e32 v140, v140, v141
	v_mul_f32_e32 v141, v121, v121
	v_mul_f32_e32 v142, v123, v123
	v_fmac_f32_e32 v141, v120, v120
	v_fmac_f32_e32 v142, v122, v122
	v_add_f32_e32 v141, v141, v142
	v_add_f32_e32 v140, v140, v141
	v_mul_f32_e32 v141, v125, v125
	v_mul_f32_e32 v142, v127, v127
	v_fmac_f32_e32 v141, v124, v124
	v_fmac_f32_e32 v142, v126, v126
	v_add_f32_e32 v141, v141, v142
	v_add_f32_e32 v140, v140, v141
	s_nop 1
	v_add_f32_dpp v140, v140, v140 quad_perm:[1,0,3,2] row_mask:0xf bank_mask:0xf
	s_nop 1
	v_add_f32_dpp v140, v140, v140 quad_perm:[2,3,0,1] row_mask:0xf bank_mask:0xf
	s_nop 1
	v_add_f32_dpp v140, v140, v140 row_half_mirror row_mask:0xf bank_mask:0xf
	s_nop 1
	v_add_f32_dpp v140, v140, v140 row_mirror row_mask:0xf bank_mask:0xf
	s_nop 0
	v_readlane_b32 s24, v140, 0
	v_readlane_b32 s25, v140, 16
	v_readlane_b32 s26, v140, 32
	v_readlane_b32 s27, v140, 48
	v_mov_b32_e32 v141, s24
	v_mov_b32_e32 v142, s26
	v_add_f32_e32 v141, s25, v141
	v_add_f32_e32 v142, s27, v142
	v_add_f32_e32 v140, v141, v142
	v_fmamk_f32 v140, v140, 0x3a800000, v143
	v_sqrt_f32_e32 v132, v140
	s_nop 0
	v_add_u32_e32 v133, -1, v132
	v_add_u32_e32 v134, 1, v132
	v_fma_f32 v135, -v133, v132, v140
	v_fma_f32 v136, -v134, v132, v140
	v_cmp_ge_f32_e64 s[20:21], 0, v135
	s_nop 1
	v_cndmask_b32_e64 v132, v132, v133, s[20:21]
	v_cmp_lt_f32_e64 s[20:21], 0, v136
	s_nop 1
	v_cndmask_b32_e64 v132, v132, v134, s[20:21]
	v_div_scale_f32 v133, s[20:21], v132, v132, 1.0
	v_rcp_f32_e32 v134, v133
	v_div_scale_f32 v135, vcc, 1.0, v132, 1.0
	v_fma_f32 v136, -v133, v134, 1.0
	v_fmac_f32_e32 v134, v136, v134
	v_mul_f32_e32 v136, v135, v134
	v_fma_f32 v137, -v133, v136, v135
	v_fmac_f32_e32 v136, v137, v134
	v_fma_f32 v133, -v133, v136, v135
	s_nop 1
	v_div_fmas_f32 v133, v133, v134, v136
	v_div_fixup_f32 v140, v133, v132, 1.0
	s_mul_i32 s0, s5, 2
	s_add_i32 s0, s0, s35
	s_lshl_b32 s0, s0, 2
	s_add_u32 s18, s74, s0
	s_addc_u32 s19, s75, 0
	s_mov_b64 s[30:31], exec
	s_mov_b64 exec, 1
	global_store_dword v6, v140, s[18:19]
	s_mov_b64 exec, s[30:31]
	s_waitcnt vmcnt(15)
	v_lshlrev_b32_e32 v96, 16, v64
	v_and_b32_e32 v97, 0xffff0000, v64
	v_lshlrev_b32_e32 v98, 16, v65
	v_and_b32_e32 v99, 0xffff0000, v65
	v_lshlrev_b32_e32 v100, 16, v66
	v_and_b32_e32 v101, 0xffff0000, v66
	v_lshlrev_b32_e32 v102, 16, v67
	v_and_b32_e32 v103, 0xffff0000, v67
	v_lshlrev_b32_e32 v104, 16, v68
	v_and_b32_e32 v105, 0xffff0000, v68
	v_lshlrev_b32_e32 v106, 16, v69
	v_and_b32_e32 v107, 0xffff0000, v69
	v_lshlrev_b32_e32 v108, 16, v70
	v_and_b32_e32 v109, 0xffff0000, v70
	v_lshlrev_b32_e32 v110, 16, v71
	v_and_b32_e32 v111, 0xffff0000, v71
	v_mul_f32_e32 v129, v97, v97
	v_mul_f32_e32 v130, v99, v99
	v_fmac_f32_e32 v129, v96, v96
	v_fmac_f32_e32 v130, v98, v98
	v_add_f32_e32 v128, v129, v130
	v_mul_f32_e32 v129, v101, v101
	v_mul_f32_e32 v130, v103, v103
	v_fmac_f32_e32 v129, v100, v100
	v_fmac_f32_e32 v130, v102, v102
	v_add_f32_e32 v129, v129, v130
	v_add_f32_e32 v128, v128, v129
	v_mul_f32_e32 v129, v105, v105
	v_mul_f32_e32 v130, v107, v107
	v_fmac_f32_e32 v129, v104, v104
	v_fmac_f32_e32 v130, v106, v106
	v_add_f32_e32 v129, v129, v130
	v_add_f32_e32 v128, v128, v129
	v_mul_f32_e32 v129, v109, v109
	v_mul_f32_e32 v130, v111, v111
	v_fmac_f32_e32 v129, v108, v108
	v_fmac_f32_e32 v130, v110, v110
	v_add_f32_e32 v129, v129, v130
	v_add_f32_e32 v128, v128, v129
	v_lshlrev_b32_e32 v112, 16, v72
	v_and_b32_e32 v113, 0xffff0000, v72
	v_lshlrev_b32_e32 v114, 16, v73
	v_and_b32_e32 v115, 0xffff0000, v73
	v_lshlrev_b32_e32 v116, 16, v74
	v_and_b32_e32 v117, 0xffff0000, v74
	v_lshlrev_b32_e32 v118, 16, v75
	v_and_b32_e32 v119, 0xffff0000, v75
	v_lshlrev_b32_e32 v120, 16, v76
	v_and_b32_e32 v121, 0xffff0000, v76
	v_lshlrev_b32_e32 v122, 16, v77
	v_and_b32_e32 v123, 0xffff0000, v77
	v_lshlrev_b32_e32 v124, 16, v78
	v_and_b32_e32 v125, 0xffff0000, v78
	v_lshlrev_b32_e32 v126, 16, v79
	v_and_b32_e32 v127, 0xffff0000, v79
	v_add_f32_dpp v128, v128, v128 quad_perm:[1,0,3,2] row_mask:0xf bank_mask:0xf
	s_nop 1
	v_add_f32_dpp v128, v128, v128 quad_perm:[2,3,0,1] row_mask:0xf bank_mask:0xf
	s_nop 1
	v_add_f32_dpp v128, v128, v128 row_half_mirror row_mask:0xf bank_mask:0xf
	s_nop 1
	v_add_f32_dpp v128, v128, v128 row_mirror row_mask:0xf bank_mask:0xf
	s_nop 0
	v_readlane_b32 s24, v128, 0
	v_readlane_b32 s25, v128, 16
	v_readlane_b32 s26, v128, 32
	v_readlane_b32 s27, v128, 48
	v_mov_b32_e32 v129, s24
	v_mov_b32_e32 v130, s26
	v_add_f32_e32 v129, s25, v129
	v_add_f32_e32 v130, s27, v130
	v_add_f32_e32 v128, v129, v130
	v_fmamk_f32 v128, v128, 0x3a800000, v143
	v_sqrt_f32_e32 v132, v128
	s_nop 0
	v_add_u32_e32 v133, -1, v132
	v_add_u32_e32 v134, 1, v132
	v_fma_f32 v135, -v133, v132, v128
	v_fma_f32 v136, -v134, v132, v128
	v_cmp_ge_f32_e64 s[20:21], 0, v135
	s_nop 1
	v_cndmask_b32_e64 v132, v132, v133, s[20:21]
	v_cmp_lt_f32_e64 s[20:21], 0, v136
	s_nop 1
	v_cndmask_b32_e64 v132, v132, v134, s[20:21]
	v_div_scale_f32 v133, s[20:21], v132, v132, 1.0
	v_rcp_f32_e32 v134, v133
	v_div_scale_f32 v135, vcc, 1.0, v132, 1.0
	v_fma_f32 v136, -v133, v134, 1.0
	v_fmac_f32_e32 v134, v136, v134
	v_mul_f32_e32 v136, v135, v134
	v_fma_f32 v137, -v133, v136, v135
	v_fmac_f32_e32 v136, v137, v134
	v_fma_f32 v133, -v133, v136, v135
	s_nop 1
	v_div_fmas_f32 v133, v133, v134, v136
	v_div_fixup_f32 v128, v133, v132, 1.0
	v_pk_mul_f32 v[96:97], v[96:97], v[128:129] op_sel_hi:[1,0]
	v_pk_mul_f32 v[98:99], v[98:99], v[128:129] op_sel_hi:[1,0]
	v_pk_mul_f32 v[100:101], v[100:101], v[128:129] op_sel_hi:[1,0]
	v_pk_mul_f32 v[102:103], v[102:103], v[128:129] op_sel_hi:[1,0]
	v_pk_mul_f32 v[104:105], v[104:105], v[128:129] op_sel_hi:[1,0]
	v_pk_mul_f32 v[106:107], v[106:107], v[128:129] op_sel_hi:[1,0]
	v_pk_mul_f32 v[108:109], v[108:109], v[128:129] op_sel_hi:[1,0]
	v_pk_mul_f32 v[110:111], v[110:111], v[128:129] op_sel_hi:[1,0]
	v_pk_fma_f32 v[112:113], v[80:81], v[96:97], v[112:113]
	v_pk_fma_f32 v[114:115], v[82:83], v[98:99], v[114:115]
	v_pk_fma_f32 v[116:117], v[84:85], v[100:101], v[116:117]
	v_pk_fma_f32 v[118:119], v[86:87], v[102:103], v[118:119]
	v_pk_fma_f32 v[120:121], v[88:89], v[104:105], v[120:121]
	v_pk_fma_f32 v[122:123], v[90:91], v[106:107], v[122:123]
	v_pk_fma_f32 v[124:125], v[92:93], v[108:109], v[124:125]
	v_pk_fma_f32 v[126:127], v[94:95], v[110:111], v[126:127]
	v_cvt_pk_bf16_f32 v64, v112, v113
	v_cvt_pk_bf16_f32 v65, v114, v115
	v_cvt_pk_bf16_f32 v66, v116, v117
	v_cvt_pk_bf16_f32 v67, v118, v119
	v_cvt_pk_bf16_f32 v68, v120, v121
	v_cvt_pk_bf16_f32 v69, v122, v123
	v_cvt_pk_bf16_f32 v70, v124, v125
	v_cvt_pk_bf16_f32 v71, v126, v127
	global_store_dwordx2 v4, v[64:65], s[16:17] offset:0
	global_store_dwordx2 v4, v[66:67], s[16:17] offset:512
	global_store_dwordx2 v4, v[68:69], s[16:17] offset:1024
	global_store_dwordx2 v4, v[70:71], s[16:17] offset:1536
	v_mul_f32_e32 v141, v113, v113
	v_mul_f32_e32 v142, v115, v115
	v_fmac_f32_e32 v141, v112, v112
	v_fmac_f32_e32 v142, v114, v114
	v_add_f32_e32 v140, v141, v142
	v_mul_f32_e32 v141, v117, v117
	v_mul_f32_e32 v142, v119, v119
	v_fmac_f32_e32 v141, v116, v116
	v_fmac_f32_e32 v142, v118, v118
	v_add_f32_e32 v141, v141, v142
	v_add_f32_e32 v140, v140, v141
	v_mul_f32_e32 v141, v121, v121
	v_mul_f32_e32 v142, v123, v123
	v_fmac_f32_e32 v141, v120, v120
	v_fmac_f32_e32 v142, v122, v122
	v_add_f32_e32 v141, v141, v142
	v_add_f32_e32 v140, v140, v141
	v_mul_f32_e32 v141, v125, v125
	v_mul_f32_e32 v142, v127, v127
	v_fmac_f32_e32 v141, v124, v124
	v_fmac_f32_e32 v142, v126, v126
	v_add_f32_e32 v141, v141, v142
	v_add_f32_e32 v140, v140, v141
	s_nop 1
	v_add_f32_dpp v140, v140, v140 quad_perm:[1,0,3,2] row_mask:0xf bank_mask:0xf
	s_nop 1
	v_add_f32_dpp v140, v140, v140 quad_perm:[2,3,0,1] row_mask:0xf bank_mask:0xf
	s_nop 1
	v_add_f32_dpp v140, v140, v140 row_half_mirror row_mask:0xf bank_mask:0xf
	s_nop 1
	v_add_f32_dpp v140, v140, v140 row_mirror row_mask:0xf bank_mask:0xf
	s_nop 0
	v_readlane_b32 s24, v140, 0
	v_readlane_b32 s25, v140, 16
	v_readlane_b32 s26, v140, 32
	v_readlane_b32 s27, v140, 48
	v_mov_b32_e32 v141, s24
	v_mov_b32_e32 v142, s26
	v_add_f32_e32 v141, s25, v141
	v_add_f32_e32 v142, s27, v142
	v_add_f32_e32 v140, v141, v142
	v_fmamk_f32 v140, v140, 0x3a800000, v143
	v_sqrt_f32_e32 v132, v140
	s_nop 0
	v_add_u32_e32 v133, -1, v132
	v_add_u32_e32 v134, 1, v132
	v_fma_f32 v135, -v133, v132, v140
	v_fma_f32 v136, -v134, v132, v140
	v_cmp_ge_f32_e64 s[20:21], 0, v135
	s_nop 1
	v_cndmask_b32_e64 v132, v132, v133, s[20:21]
	v_cmp_lt_f32_e64 s[20:21], 0, v136
	s_nop 1
	v_cndmask_b32_e64 v132, v132, v134, s[20:21]
	v_div_scale_f32 v133, s[20:21], v132, v132, 1.0
	v_rcp_f32_e32 v134, v133
	v_div_scale_f32 v135, vcc, 1.0, v132, 1.0
	v_fma_f32 v136, -v133, v134, 1.0
	v_fmac_f32_e32 v134, v136, v134
	v_mul_f32_e32 v136, v135, v134
	v_fma_f32 v137, -v133, v136, v135
	v_fmac_f32_e32 v136, v137, v134
	v_fma_f32 v133, -v133, v136, v135
	s_nop 1
	v_div_fmas_f32 v133, v133, v134, v136
	v_div_fixup_f32 v140, v133, v132, 1.0
	s_mul_i32 s0, s5, 3
	s_add_i32 s0, s0, s35
	s_lshl_b32 s0, s0, 2
	s_add_u32 s18, s74, s0
	s_addc_u32 s19, s75, 0
	s_mov_b64 s[30:31], exec
	s_mov_b64 exec, 1
	global_store_dword v6, v140, s[18:19]
	s_mov_b64 exec, s[30:31]
	s_lshl_b32 s0, s5, 2
	s_add_i32 s35, s35, s0
	s_cmp_lt_i32 s35, 0xc000
	s_cbranch_scc1 .Lp4_loop
